# baseline (speedup 1.0000x reference)
; template <bool WIDE>
; __device__ __forceinline__ void outproj_tile(const Params& P, int l, int mt, int nt, char* smem) {
;     ...
; #pragma unroll 4
;     for (int q = 0; q < 16; ++q) {
;       float4 y = *(const float4*)(cs + r * CSTR + half * 64 + q * 4);
;       float4 xv = *(const float4*)(xin + q * 4);
;       float4 g = *(const float4*)(g1 + q * 4);
;       float4 o = make_float4(xv.x + g.x * y.x, xv.y + g.y * y.y, xv.z + g.z * y.z, xv.w + g.w * y.w);
;       *(float4*)(xo + q * 4) = o;
;     }
.LBB0_716:
	v_lshl_add_u64 v[144:145], v[138:139], 0, s[18:19]
	v_add_co_u32_e32 v160, vcc, 0x11f42000, v144
	v_lshl_add_u64 v[148:149], v[132:133], 0, s[18:19]
	s_nop 0
	v_addc_co_u32_e32 v161, vcc, 0, v145, vcc
	global_load_dwordx4 v[140:143], v[148:149], off nt
	global_load_dwordx4 v[144:147], v[160:161], off
	global_load_dwordx4 v[156:159], v[148:149], off offset:16 nt
	global_load_dwordx4 v[164:167], v[160:161], off offset:16
	global_load_dwordx4 v[172:175], v[148:149], off offset:32 nt
	global_load_dwordx4 v[176:179], v[160:161], off offset:32
	global_load_dwordx4 v[184:187], v[148:149], off offset:48 nt
	global_load_dwordx4 v[188:191], v[160:161], off offset:48
	global_load_dwordx4 v[196:199], v[148:149], off offset:64 nt
	global_load_dwordx4 v[200:203], v[160:161], off offset:64
	global_load_dwordx4 v[208:211], v[148:149], off offset:80 nt
	global_load_dwordx4 v[212:215], v[160:161], off offset:80
	global_load_dwordx4 v[224:227], v[148:149], off offset:96 nt
	global_load_dwordx4 v[228:231], v[160:161], off offset:96
	global_load_dwordx4 v[236:239], v[148:149], off offset:112 nt
	global_load_dwordx4 v[240:243], v[160:161], off offset:112
	ds_read_b128 v[152:155], v130
	ds_read_b128 v[168:171], v130 offset:16
	ds_read_b128 v[180:183], v130 offset:32
	ds_read_b128 v[192:195], v130 offset:48
	ds_read_b128 v[204:207], v130 offset:64
	ds_read_b128 v[216:219], v130 offset:80
	ds_read_b128 v[232:235], v130 offset:96
	ds_read_b128 v[244:247], v130 offset:112
	v_add_u32_e32 v130, 0x80, v130
	v_lshl_add_u64 v[162:163], v[136:137], 0, s[18:19]
	s_add_u32 s18, s18, 0x80
	s_addc_u32 s19, s19, 0
	s_cmpk_eq_i32 s18, 0x100
	s_waitcnt vmcnt(14) lgkmcnt(7)
	v_pk_fma_f32 v[140:141], v[152:153], v[144:145], v[140:141]
	v_pk_fma_f32 v[142:143], v[154:155], v[146:147], v[142:143]
	global_store_dwordx4 v[162:163], v[140:143], off
	s_waitcnt vmcnt(13) lgkmcnt(6)
	v_pk_fma_f32 v[156:157], v[168:169], v[164:165], v[156:157]
	v_pk_fma_f32 v[158:159], v[170:171], v[166:167], v[158:159]
	global_store_dwordx4 v[162:163], v[156:159], off offset:16
	s_waitcnt vmcnt(12) lgkmcnt(5)
	v_pk_fma_f32 v[172:173], v[180:181], v[176:177], v[172:173]
	v_pk_fma_f32 v[174:175], v[182:183], v[178:179], v[174:175]
	global_store_dwordx4 v[162:163], v[172:175], off offset:32
	s_waitcnt vmcnt(11) lgkmcnt(4)
	v_pk_fma_f32 v[184:185], v[192:193], v[188:189], v[184:185]
	v_pk_fma_f32 v[186:187], v[194:195], v[190:191], v[186:187]
	global_store_dwordx4 v[162:163], v[184:187], off offset:48
	s_waitcnt vmcnt(10) lgkmcnt(3)
	v_pk_fma_f32 v[196:197], v[204:205], v[200:201], v[196:197]
	v_pk_fma_f32 v[198:199], v[206:207], v[202:203], v[198:199]
	global_store_dwordx4 v[162:163], v[196:199], off offset:64
	s_waitcnt vmcnt(9) lgkmcnt(2)
	v_pk_fma_f32 v[208:209], v[216:217], v[212:213], v[208:209]
	v_pk_fma_f32 v[210:211], v[218:219], v[214:215], v[210:211]
	global_store_dwordx4 v[162:163], v[208:211], off offset:80
	s_waitcnt vmcnt(8) lgkmcnt(1)
	v_pk_fma_f32 v[224:225], v[232:233], v[228:229], v[224:225]
	v_pk_fma_f32 v[226:227], v[234:235], v[230:231], v[226:227]
	global_store_dwordx4 v[162:163], v[224:227], off offset:96
	s_waitcnt vmcnt(7) lgkmcnt(0)
	v_pk_fma_f32 v[236:237], v[244:245], v[240:241], v[236:237]
	v_pk_fma_f32 v[238:239], v[246:247], v[242:243], v[238:239]
	global_store_dwordx4 v[162:163], v[236:239], off offset:112
	s_cbranch_scc0 .LBB0_716
	s_mov_b32 s15, 1
	s_mov_b64 s[18:19], 0
	s_and_b64 vcc, exec, s[20:21]
	s_barrier
	s_cbranch_vccz .LBB0_709
	s_add_i32 s51, s51, s94
	s_cmpk_gt_i32 s51, 0x3ff
	s_cbranch_scc0 .LBB0_706
